# attention: band-V loads issued ~200 instructions earlier (as soon as their destination registers are free)
# speedup vs baseline: 1.0155x; 1.0001x over previous
.LBB0_1419:
	s_waitcnt lgkmcnt(3)
	v_add_f32_e32 v20, v79, v80
	v_fmamk_f32 v20, v20, 0x3c800000, v106
	v_rsq_f32_e32 v20, v20
	v_max_i32_e32 v21, 8, v76
	v_add_u32_e32 v45, -8, v21
	s_max_i32 s0, s2, 4
	v_mul_f32_e32 v44, 0x3e38aa3b, v20
	v_pk_mul_f32 v[22:23], v[44:45], v[74:75] op_sel_hi:[0,1]
	s_waitcnt vmcnt(0)
	v_pk_mul_f32 v[22:23], v[36:37], v[22:23]
	v_pk_mul_f32 v[20:21], v[44:45], v[64:65] op_sel_hi:[0,1]
	v_cvt_pk_f16_f32 v24, v22, v23
	v_pk_mul_f32 v[22:23], v[44:45], v[60:61] op_sel_hi:[0,1]
	v_pk_mul_f32 v[20:21], v[40:41], v[20:21]
	v_pk_mul_f32 v[22:23], v[42:43], v[22:23]
	v_cvt_pk_f16_f32 v20, v20, v21
	v_cvt_pk_f16_f32 v21, v22, v23
	v_pk_mul_f32 v[22:23], v[44:45], v[62:63] op_sel_hi:[0,1]
	v_pk_mul_f32 v[22:23], v[38:39], v[22:23]
	v_pk_mul_f32 v[26:27], v[44:45], v[68:69] op_sel_hi:[0,1]
	v_cvt_pk_f16_f32 v25, v22, v23
	v_pk_mul_f32 v[22:23], v[44:45], v[66:67] op_sel_hi:[0,1]
	v_pk_mul_f32 v[26:27], v[28:29], v[26:27]
	v_pk_mul_f32 v[28:29], v[44:45], v[70:71] op_sel_hi:[0,1]
	v_pk_mul_f32 v[22:23], v[32:33], v[22:23]
	v_pk_mul_f32 v[28:29], v[34:35], v[28:29]
	s_add_i32 s0, s0, -4
	v_cvt_pk_f16_f32 v22, v22, v23
	v_cvt_pk_f16_f32 v23, v28, v29
	v_pk_mul_f32 v[28:29], v[44:45], v[72:73] op_sel_hi:[0,1]
	s_min_u32 s0, s0, 0x78
	v_pk_mul_f32 v[28:29], v[30:31], v[28:29]
	s_sub_i32 s3, s0, s41
	v_cvt_pk_f16_f32 v26, v26, v27
	v_cvt_pk_f16_f32 v27, v28, v29
	v_add_u32_e32 v64, s40, v101
	v_and_b32_e32 v29, -16, v77
	s_lshl_b32 s16, s3, 6
	v_add_u32_e32 v65, 0, v29
	v_add_u32_e32 v30, s16, v64
	s_waitcnt lgkmcnt(0)
	s_barrier
	v_mad_i32_i24 v38, v30, s25, v65
	ds_read_b128 v[30:33], v38
	ds_read_b128 v[34:37], v38 offset:64
	v_lshlrev_b32_e32 v100, 2, v78
	v_add_u32_e32 v42, s40, v100
	v_min_u32_e32 v60, 48, v45
	v_add_u32_e32 v28, 16, v42
	v_cmp_ge_i32_e32 vcc, v28, v60
	v_sub_u32_e32 v28, v28, v76
	v_max_i32_e32 v28, -15, v28
	v_add_u32_e32 v28, 15, v28
	s_sub_i32 s2, s0, s2
	v_min_u32_e32 v43, 30, v28
	v_sub_u32_e32 v28, v42, v76
	s_mulk_i32 s2, 0x7c
	v_max_i32_e32 v28, -15, v28
	s_add_i32 s2, s2, 0
	s_waitcnt lgkmcnt(1)
	v_mfma_f32_16x16x32_f16 v[30:33], v[30:33], v[24:27], 0
	v_add_u32_e32 v28, 15, v28
	s_add_i32 s45, s2, 0x26764
	v_min_u32_e32 v28, 30, v28
	v_lshl_add_u32 v62, v28, 2, s45
	ds_read2_b32 v[44:45], v62 offset1:31
	s_waitcnt lgkmcnt(1)
	v_mfma_f32_16x16x32_f16 v[30:33], v[34:37], v[20:23], v[30:33]
	v_or_b32_e32 v34, 1, v42
	v_add_u32_e32 v61, 16, v60
	v_cmp_ge_i32_e64 s[2:3], v42, v60
	v_cmp_lt_i32_e64 s[4:5], v42, v61
	s_and_b64 s[2:3], s[2:3], s[4:5]
	s_waitcnt lgkmcnt(0)
	s_nop 1
	v_add_f32_e32 v28, v30, v44
	v_sub_u32_e32 v30, v34, v76
	v_max_i32_e32 v30, -15, v30
	v_add_u32_e32 v30, 15, v30
	v_min_u32_e32 v30, 30, v30
	v_lshl_add_u32 v63, v30, 2, s45
	v_cndmask_b32_e64 v30, v107, 0, s[2:3]
	v_cmp_ge_i32_e64 s[2:3], v34, v60
	v_cmp_lt_i32_e64 s[4:5], v34, v61
	v_or_b32_e32 v34, 2, v42
	v_sub_u32_e32 v35, v34, v76
	ds_read2_b32 v[46:47], v63 offset1:31
	s_and_b64 s[2:3], s[2:3], s[4:5]
	v_max_i32_e32 v35, -15, v35
	v_or_b32_e32 v39, 3, v42
	v_add_f32_e32 v127, v30, v28
	v_cndmask_b32_e64 v28, v107, 0, s[2:3]
	v_add_u32_e32 v35, 15, v35
	v_cmp_ge_i32_e64 s[2:3], v34, v60
	v_cmp_lt_i32_e64 s[4:5], v34, v61
	v_sub_u32_e32 v34, v39, v76
	v_min_u32_e32 v35, 30, v35
	v_max_i32_e32 v34, -15, v34
	v_lshl_add_u32 v66, v35, 2, s45
	v_add_u32_e32 v34, 15, v34
	ds_read2_b32 v[48:49], v66 offset1:31
	v_min_u32_e32 v34, 30, v34
	s_waitcnt lgkmcnt(1)
	v_add_f32_e32 v31, v31, v46
	s_and_b64 s[2:3], s[2:3], s[4:5]
	v_lshl_add_u32 v67, v34, 2, s45
	v_add_f32_e32 v128, v28, v31
	v_cndmask_b32_e64 v31, v107, 0, s[2:3]
	ds_read2_b32 v[50:51], v67 offset1:31
	ds_read_b128 v[34:37], v38 offset:2304
	v_cmp_ge_i32_e64 s[2:3], v39, v60
	v_cmp_lt_i32_e64 s[4:5], v39, v61
	ds_read_b128 v[38:41], v38 offset:2368
	s_waitcnt lgkmcnt(3)
	v_add_f32_e32 v32, v32, v48
	s_and_b64 s[2:3], s[2:3], s[4:5]
	v_add_f32_e32 v129, v31, v32
	s_waitcnt lgkmcnt(2)
	v_add_f32_e32 v32, v33, v50
	v_cndmask_b32_e64 v154, v107, 0, s[2:3]
	v_add_f32_e32 v130, v154, v32
	s_waitcnt lgkmcnt(1)
	v_mfma_f32_16x16x32_f16 v[32:35], v[34:37], v[24:27], 0
	v_add_u32_e32 v37, 17, v42
	v_lshl_add_u32 v68, v43, 2, s45
	ds_read2_b32 v[52:53], v68 offset1:31
	s_waitcnt lgkmcnt(1)
	v_mfma_f32_16x16x32_f16 v[32:35], v[38:41], v[20:23], v[32:35]
	v_sub_u32_e32 v38, v37, v76
	v_max_i32_e32 v38, -15, v38
	v_add_u32_e32 v38, 15, v38
	v_min_u32_e32 v38, 30, v38
	v_lshl_add_u32 v69, v38, 2, s45
	ds_read2_b32 v[54:55], v69 offset1:31
	v_cmp_lt_i32_e64 s[0:1], v42, v60
	s_and_b64 s[0:1], s[0:1], vcc
	s_waitcnt lgkmcnt(1)
	v_add_f32_e32 v32, v32, v52
	v_cndmask_b32_e64 v156, v107, 0, s[0:1]
	v_add_f32_e32 v131, v156, v32
	s_waitcnt lgkmcnt(0)
	v_add_f32_e32 v32, v33, v54
	v_add_u32_e32 v33, 18, v42
	v_cmp_ge_i32_e32 vcc, v37, v60
	v_cmp_lt_i32_e64 s[0:1], v37, v61
	v_sub_u32_e32 v37, v33, v76
	v_max_i32_e32 v37, -15, v37
	v_add_u32_e32 v37, 15, v37
	v_min_u32_e32 v37, 30, v37
	v_lshl_add_u32 v70, v37, 2, s45
	ds_read2_b32 v[56:57], v70 offset1:31
	s_and_b64 s[0:1], vcc, s[0:1]
	v_max3_f32 v44, v127, s34, v128
	v_cndmask_b32_e64 v158, v107, 0, s[0:1]
	v_max3_f32 v36, v44, v129, v130
	v_add_f32_e32 v132, v158, v32
	s_add_i32 s4, s16, 64
	v_max3_f32 v44, v36, v131, v132
	v_cmp_ge_i32_e32 vcc, v33, v60
	v_cmp_lt_i32_e64 s[0:1], v33, v61
	v_add_u32_e32 v33, 19, v42
	v_add_u32_e32 v36, s4, v64
	s_waitcnt lgkmcnt(0)
	v_add_f32_e32 v32, v34, v56
	v_sub_u32_e32 v34, v33, v76
	v_mad_i32_i24 v46, v36, s25, v65
	v_max_i32_e32 v34, -15, v34
	ds_read_b128 v[36:39], v46
	ds_read_b128 v[40:43], v46 offset:64
	v_add_u32_e32 v34, 15, v34
	v_min_u32_e32 v34, 30, v34
	v_lshl_add_u32 v71, v34, 2, s45
	ds_read2_b32 v[58:59], v71 offset1:31
	s_and_b64 s[0:1], vcc, s[0:1]
	v_cndmask_b32_e64 v160, v107, 0, s[0:1]
	v_add_f32_e32 v133, v160, v32
	v_cmp_ge_i32_e32 vcc, v33, v60
	v_cmp_lt_i32_e64 s[0:1], v33, v61
	s_waitcnt lgkmcnt(0)
	v_add_f32_e32 v48, v35, v58
	v_mfma_f32_16x16x32_f16 v[32:35], v[36:39], v[24:27], 0
	ds_read_b128 v[36:39], v46 offset:2304
	s_and_b64 s[0:1], vcc, s[0:1]
	v_cndmask_b32_e64 v170, v107, 0, s[0:1]
	v_mfma_f32_16x16x32_f16 v[32:35], v[40:43], v[20:23], v[32:35]
	ds_read_b128 v[40:43], v46 offset:2368
	v_add_f32_e32 v134, v170, v48
	v_max3_f32 v44, v44, v133, v134
	s_waitcnt lgkmcnt(1)
	v_mfma_f32_16x16x32_f16 v[36:39], v[36:39], v[24:27], 0
	s_add_i32 s5, s16, 0x80
	s_nop 1
	v_add_f32_e32 v32, v32, v45
	v_add_f32_e32 v136, v30, v32
	v_add_f32_e32 v32, v33, v47
	v_add_f32_e32 v33, v34, v49
	v_add_f32_e32 v137, v28, v32
	v_add_f32_e32 v138, v31, v33
	v_add_f32_e32 v33, v35, v51
	v_max3_f32 v32, v44, v136, v137
	v_add_f32_e32 v139, v154, v33
	v_max3_f32 v44, v32, v138, v139
	s_waitcnt lgkmcnt(0)
	v_mfma_f32_16x16x32_f16 v[32:35], v[40:43], v[20:23], v[36:39]
	s_add_i32 s45, s16, 0xc0
	s_add_i32 s46, s16, 0x100
	s_add_i32 s47, s16, 0x140
	s_add_i32 s48, s16, 0x180
	s_add_i32 s49, s16, 0x1c0
	s_nop 2
	v_add_f32_e32 v32, v32, v53
	v_add_f32_e32 v135, v156, v32
	v_add_u32_e32 v32, s5, v64
	v_mad_i32_i24 v52, v32, s25, v65
	ds_read_b128 v[36:39], v52
	ds_read_b128 v[40:43], v52 offset:64
	v_add_f32_e32 v32, v33, v55
	v_add_f32_e32 v140, v158, v32
	v_add_f32_e32 v32, v34, v57
	v_add_f32_e32 v142, v160, v32
	v_add_f32_e32 v32, v35, v59
	v_add_f32_e32 v141, v170, v32
	s_waitcnt lgkmcnt(1)
	v_mfma_f32_16x16x32_f16 v[32:35], v[36:39], v[24:27], 0
	v_max3_f32 v44, v44, v135, v140
	v_max3_f32 v53, v44, v142, v141
	ds_read2_b32 v[44:45], v62 offset0:62 offset1:93
	ds_read2_b32 v[46:47], v63 offset0:62 offset1:93
	s_waitcnt lgkmcnt(2)
	v_mfma_f32_16x16x32_f16 v[32:35], v[40:43], v[20:23], v[32:35]
	ds_read_b128 v[36:39], v52 offset:2304
	ds_read2_b32 v[48:49], v66 offset0:62 offset1:93
	ds_read2_b32 v[50:51], v67 offset0:62 offset1:93
	ds_read_b128 v[40:43], v52 offset:2368
	ds_read2_b32 v[54:55], v69 offset0:62 offset1:93
	s_waitcnt lgkmcnt(6)
	s_nop 1
	v_add_f32_e32 v32, v32, v44
	v_add_f32_e32 v143, v30, v32
	s_waitcnt lgkmcnt(5)
	v_add_f32_e32 v32, v33, v46
	v_add_f32_e32 v144, v28, v32
	s_waitcnt lgkmcnt(3)
	v_add_f32_e32 v32, v34, v48
	v_add_f32_e32 v145, v31, v32
	s_waitcnt lgkmcnt(2)
	v_add_f32_e32 v46, v35, v50
	v_mfma_f32_16x16x32_f16 v[32:35], v[36:39], v[24:27], 0
	v_max3_f32 v44, v53, v143, v144
	ds_read2_b32 v[52:53], v68 offset0:62 offset1:93
	v_add_f32_e32 v146, v154, v46
	s_waitcnt lgkmcnt(2)
	v_mfma_f32_16x16x32_f16 v[32:35], v[40:43], v[20:23], v[32:35]
	ds_read2_b32 v[56:57], v70 offset0:62 offset1:93
	v_max3_f32 v44, v44, v145, v146
	s_waitcnt lgkmcnt(1)
	s_nop 4
	v_add_f32_e32 v32, v32, v52
	v_add_f32_e32 v147, v156, v32
	v_add_u32_e32 v32, s45, v64
	v_mad_i32_i24 v46, v32, s25, v65
	ds_read_b128 v[36:39], v46
	ds_read_b128 v[40:43], v46 offset:64
	ds_read2_b32 v[58:59], v71 offset0:62 offset1:93
	s_waitcnt lgkmcnt(2)
	v_mfma_f32_16x16x32_f16 v[36:39], v[36:39], v[24:27], 0
	v_add_f32_e32 v32, v33, v54
	v_add_f32_e32 v33, v34, v56
	v_add_f32_e32 v148, v158, v32
	v_add_f32_e32 v149, v160, v33
	s_waitcnt lgkmcnt(0)
	v_add_f32_e32 v33, v35, v58
	v_max3_f32 v32, v44, v147, v148
	v_add_f32_e32 v150, v170, v33
	v_max3_f32 v44, v32, v149, v150
	v_mfma_f32_16x16x32_f16 v[32:35], v[40:43], v[20:23], v[36:39]
	ds_read_b128 v[40:43], v46 offset:2368
	s_nop 1
	ds_read_b128 v[36:39], v46 offset:2304
	s_waitcnt lgkmcnt(0)
	v_mfma_f32_16x16x32_f16 v[36:39], v[36:39], v[24:27], 0
	s_nop 1
	v_add_f32_e32 v32, v32, v45
	v_add_f32_e32 v152, v30, v32
	v_add_f32_e32 v32, v33, v47
	v_add_f32_e32 v33, v34, v49
	v_add_f32_e32 v153, v28, v32
	v_add_f32_e32 v155, v31, v33
	v_add_f32_e32 v33, v35, v51
	v_max3_f32 v32, v44, v152, v153
	v_add_f32_e32 v157, v154, v33
	v_max3_f32 v44, v32, v155, v157
	v_mfma_f32_16x16x32_f16 v[32:35], v[40:43], v[20:23], v[36:39]
	s_nop 7
	v_add_f32_e32 v32, v32, v53
	v_add_f32_e32 v151, v156, v32
	v_add_u32_e32 v32, s46, v64
	v_mad_i32_i24 v52, v32, s25, v65
	ds_read_b128 v[36:39], v52
	ds_read_b128 v[40:43], v52 offset:64
	v_add_f32_e32 v32, v33, v55
	v_add_f32_e32 v159, v158, v32
	v_add_f32_e32 v32, v34, v57
	v_add_f32_e32 v192, v160, v32
	v_add_f32_e32 v32, v35, v59
	v_add_f32_e32 v161, v170, v32
	s_waitcnt lgkmcnt(1)
	v_mfma_f32_16x16x32_f16 v[32:35], v[36:39], v[24:27], 0
	v_max3_f32 v44, v44, v151, v159
	v_max3_f32 v53, v44, v192, v161
	ds_read2_b32 v[44:45], v62 offset0:124 offset1:155
	ds_read2_b32 v[46:47], v63 offset0:124 offset1:155
	s_waitcnt lgkmcnt(2)
	v_mfma_f32_16x16x32_f16 v[32:35], v[40:43], v[20:23], v[32:35]
	ds_read_b128 v[36:39], v52 offset:2304
	ds_read2_b32 v[48:49], v66 offset0:124 offset1:155
	ds_read2_b32 v[50:51], v67 offset0:124 offset1:155
	ds_read_b128 v[40:43], v52 offset:2368
	ds_read2_b32 v[54:55], v69 offset0:124 offset1:155
	s_waitcnt lgkmcnt(6)
	s_nop 1
	v_add_f32_e32 v32, v32, v44
	v_add_f32_e32 v193, v30, v32
	s_waitcnt lgkmcnt(5)
	v_add_f32_e32 v32, v33, v46
	v_add_f32_e32 v194, v28, v32
	s_waitcnt lgkmcnt(3)
	v_add_f32_e32 v32, v34, v48
	v_add_f32_e32 v195, v31, v32
	s_waitcnt lgkmcnt(2)
	v_add_f32_e32 v46, v35, v50
	v_mfma_f32_16x16x32_f16 v[32:35], v[36:39], v[24:27], 0
	v_max3_f32 v44, v53, v193, v194
	ds_read2_b32 v[52:53], v68 offset0:124 offset1:155
	v_add_f32_e32 v196, v154, v46
	s_waitcnt lgkmcnt(2)
	v_mfma_f32_16x16x32_f16 v[32:35], v[40:43], v[20:23], v[32:35]
	ds_read2_b32 v[56:57], v70 offset0:124 offset1:155
	v_max3_f32 v44, v44, v195, v196
	s_waitcnt lgkmcnt(1)
	s_nop 4
	v_add_f32_e32 v32, v32, v52
	v_add_f32_e32 v197, v156, v32
	v_add_u32_e32 v32, s47, v64
	v_mad_i32_i24 v46, v32, s25, v65
	ds_read_b128 v[36:39], v46
	ds_read_b128 v[40:43], v46 offset:64
	ds_read2_b32 v[58:59], v71 offset0:124 offset1:155
	s_waitcnt lgkmcnt(2)
	v_mfma_f32_16x16x32_f16 v[36:39], v[36:39], v[24:27], 0
	v_add_f32_e32 v32, v33, v54
	v_add_f32_e32 v33, v34, v56
	v_add_f32_e32 v198, v158, v32
	v_add_f32_e32 v199, v160, v33
	s_waitcnt lgkmcnt(0)
	v_add_f32_e32 v33, v35, v58
	v_max3_f32 v32, v44, v197, v198
	v_add_f32_e32 v200, v170, v33
	v_max3_f32 v44, v32, v199, v200
	v_mfma_f32_16x16x32_f16 v[32:35], v[40:43], v[20:23], v[36:39]
	ds_read_b128 v[40:43], v46 offset:2368
	ds_read2_b32 v[60:61], v62 offset0:186 offset1:217
	s_nop 0
	ds_read_b128 v[36:39], v46 offset:2304
	s_waitcnt lgkmcnt(0)
	v_mfma_f32_16x16x32_f16 v[36:39], v[36:39], v[24:27], 0
	s_nop 1
	v_add_f32_e32 v32, v32, v45
	v_add_f32_e32 v201, v30, v32
	v_add_f32_e32 v32, v33, v47
	v_add_f32_e32 v33, v34, v49
	v_add_f32_e32 v202, v28, v32
	v_add_f32_e32 v203, v31, v33
	v_add_f32_e32 v33, v35, v51
	v_max3_f32 v32, v44, v201, v202
	v_add_f32_e32 v206, v154, v33
	v_max3_f32 v44, v32, v203, v206
	v_mfma_f32_16x16x32_f16 v[32:35], v[40:43], v[20:23], v[36:39]
	s_nop 2
	v_add_u32_e32 v36, s48, v64
	v_mad_i32_i24 v45, v36, s25, v65
	ds_read_b128 v[36:39], v45
	ds_read_b128 v[40:43], v45 offset:64
	s_nop 0
	v_add_f32_e32 v32, v32, v53
	v_add_f32_e32 v207, v156, v32
	v_add_f32_e32 v32, v33, v55
	v_add_f32_e32 v208, v158, v32
	v_add_f32_e32 v32, v34, v57
	v_add_f32_e32 v209, v160, v32
	v_add_f32_e32 v46, v35, v59
	s_waitcnt lgkmcnt(1)
	v_mfma_f32_16x16x32_f16 v[32:35], v[36:39], v[24:27], 0
	ds_read_b128 v[36:39], v45 offset:2304
	v_max3_f32 v44, v44, v207, v208
	v_add_f32_e32 v210, v170, v46
	s_waitcnt lgkmcnt(1)
	v_mfma_f32_16x16x32_f16 v[32:35], v[40:43], v[20:23], v[32:35]
	v_max3_f32 v52, v44, v209, v210
	ds_read2_b32 v[62:63], v63 offset0:186 offset1:217
	ds_read_b128 v[40:43], v45 offset:2368
	s_waitcnt lgkmcnt(2)
	v_mfma_f32_16x16x32_f16 v[36:39], v[36:39], v[24:27], 0
	s_nop 2
	v_add_f32_e32 v32, v32, v60
	v_add_f32_e32 v211, v30, v32
	v_add_u32_e32 v32, s49, v64
	v_mad_i32_i24 v32, v32, s25, v65
	ds_read_b128 v[44:47], v32
	ds_read2_b32 v[64:65], v66 offset0:186 offset1:217
	ds_read_b128 v[48:51], v32 offset:64
	s_waitcnt lgkmcnt(4)
	v_add_f32_e32 v33, v33, v62
	s_waitcnt lgkmcnt(3)
	v_mfma_f32_16x16x32_f16 v[36:39], v[40:43], v[20:23], v[36:39]
	ds_read_b128 v[40:43], v32 offset:2304
	v_add_f32_e32 v212, v28, v33
	v_max3_f32 v56, v52, v211, v212
	s_waitcnt lgkmcnt(3)
	v_mfma_f32_16x16x32_f16 v[44:47], v[44:47], v[24:27], 0
	ds_read2_b32 v[66:67], v67 offset0:186 offset1:217
	ds_read_b128 v[52:55], v32 offset:2368
	v_mul_u32_u24_e32 v32, 0x90, v101
	v_add3_u32 v171, s26, v29, v32
	s_waitcnt lgkmcnt(3)
	v_mfma_f32_16x16x32_f16 v[44:47], v[48:51], v[20:23], v[44:47]
	ds_read_b128 v[48:51], v171
	v_add_f32_e32 v33, v34, v64
	v_add_f32_e32 v213, v31, v33
	s_waitcnt lgkmcnt(2)
	v_add_f32_e32 v29, v35, v66
	ds_read_b128 v[32:35], v171 offset:64
	v_mfma_f32_16x16x32_f16 v[40:43], v[40:43], v[24:27], 0
	v_add_f32_e32 v214, v154, v29
	v_max3_f32 v29, v56, v213, v214
	s_waitcnt lgkmcnt(2)
	v_mfma_f32_16x16x32_f16 v[40:43], v[52:55], v[20:23], v[40:43]
	ds_read2_b32 v[162:163], v68 offset0:186 offset1:217
	ds_read_b128 v[52:55], v171 offset:2304
	ds_read2_b32 v[164:165], v69 offset0:186 offset1:217
	ds_read_b128 v[56:59], v171 offset:2368
	ds_read2_b32 v[166:167], v70 offset0:186 offset1:217
	s_waitcnt lgkmcnt(6)
	v_mfma_f32_16x16x32_f16 v[48:51], v[48:51], v[24:27], 0
	ds_read2_b32 v[168:169], v71 offset0:186 offset1:217
	s_waitcnt lgkmcnt(5)
	v_add_f32_e32 v40, v40, v163
	v_add_f32_e32 v223, v156, v40
	v_mfma_f32_16x16x32_f16 v[84:87], v[32:35], v[20:23], v[48:51]
	v_add_f32_e32 v32, v36, v162
	v_add_f32_e32 v215, v156, v32
	ds_read_b128 v[32:35], v171 offset:4608
	s_waitcnt lgkmcnt(5)
	v_mfma_f32_16x16x32_f16 v[48:51], v[52:55], v[24:27], 0
	ds_read_b128 v[52:55], v171 offset:4672
	s_waitcnt lgkmcnt(5)
	v_add_f32_e32 v36, v37, v164
	v_add_f32_e32 v216, v158, v36
	s_waitcnt lgkmcnt(4)
	v_mfma_f32_16x16x32_f16 v[80:83], v[56:59], v[20:23], v[48:51]
	ds_read_b128 v[56:59], v171 offset:6976
	s_waitcnt lgkmcnt(4)
	v_add_f32_e32 v36, v38, v166
	v_add_f32_e32 v217, v160, v36
	ds_read_b128 v[48:51], v171 offset:6912
	s_waitcnt lgkmcnt(3)
	v_mfma_f32_16x16x32_f16 v[32:35], v[32:35], v[24:27], 0
	v_max3_f32 v29, v29, v215, v216
	s_waitcnt lgkmcnt(2)
	v_mfma_f32_16x16x32_f16 v[76:79], v[52:55], v[20:23], v[32:35]
	v_add_f32_e32 v52, v39, v168
	v_add_f32_e32 v218, v170, v52
	ds_read_b128 v[52:55], v171 offset:11584
	s_nop 1
	ds_read_b128 v[32:35], v171 offset:9216
	s_waitcnt lgkmcnt(2)
	v_mfma_f32_16x16x32_f16 v[36:39], v[48:51], v[24:27], 0
	ds_read_b128 v[48:51], v171 offset:9280
	v_max3_f32 v29, v29, v217, v218
	v_mfma_f32_16x16x32_f16 v[72:75], v[56:59], v[20:23], v[36:39]
	s_waitcnt lgkmcnt(1)
	v_mfma_f32_16x16x32_f16 v[32:35], v[32:35], v[24:27], 0
	s_nop 2
	v_add_f32_e32 v36, v44, v61
	v_add_f32_e32 v219, v30, v36
	ds_read_b128 v[36:39], v171 offset:11520
	s_waitcnt lgkmcnt(1)
	v_mfma_f32_16x16x32_f16 v[68:71], v[48:51], v[20:23], v[32:35]
	v_add_f32_e32 v30, v45, v63
	v_add_f32_e32 v220, v28, v30
	v_add_f32_e32 v28, v46, v65
	ds_read_b128 v[32:35], v171 offset:13824
	s_waitcnt lgkmcnt(1)
	v_mfma_f32_16x16x32_f16 v[36:39], v[36:39], v[24:27], 0
	v_max3_f32 v44, v29, v219, v220
	v_add_f32_e32 v221, v31, v28
	ds_read_b128 v[28:31], v171 offset:13888
	v_add_f32_e32 v45, v47, v67
	v_mfma_f32_16x16x32_f16 v[64:67], v[52:55], v[20:23], v[36:39]
	v_add_f32_e32 v222, v154, v45
	v_max3_f32 v48, v44, v221, v222
	ds_read_b128 v[44:47], v171 offset:16192
	ds_read_b128 v[36:39], v171 offset:16128
	s_waitcnt lgkmcnt(3)
	v_mfma_f32_16x16x32_f16 v[32:35], v[32:35], v[24:27], 0
	s_waitcnt lgkmcnt(2)
	v_mfma_f32_16x16x32_f16 v[60:63], v[28:31], v[20:23], v[32:35]
	v_add_f32_e32 v28, v41, v165
	v_add_f32_e32 v224, v158, v28
	ds_read_b128 v[28:31], v171 offset:18432
	s_waitcnt lgkmcnt(1)
	v_mfma_f32_16x16x32_f16 v[32:35], v[36:39], v[24:27], 0
	ds_read_b128 v[36:39], v171 offset:18496
	v_add_f32_e32 v41, v42, v167
	v_add_f32_e32 v225, v160, v41
	v_mfma_f32_16x16x32_f16 v[56:59], v[44:47], v[20:23], v[32:35]
	v_add_f32_e32 v41, v43, v169
	v_max3_f32 v40, v48, v223, v224
	v_add_f32_e32 v226, v170, v41
	s_nop 0
	ds_read_b128 v[32:35], v171 offset:20736
	v_max3_f32 v44, v40, v225, v226
	ds_read_b128 v[40:43], v171 offset:20800
	s_waitcnt lgkmcnt(3)
	v_mfma_f32_16x16x32_f16 v[28:31], v[28:31], v[24:27], 0
	ds_read_b128 v[162:165], v171 offset:30016
	ds_read_b128 v[166:169], v171 offset:32320
	s_waitcnt lgkmcnt(4)
	v_mfma_f32_16x16x32_f16 v[52:55], v[36:39], v[20:23], v[28:31]
	s_waitcnt lgkmcnt(3)
	v_mfma_f32_16x16x32_f16 v[32:35], v[32:35], v[24:27], 0
	s_nop 1
	v_max3_f32 v28, v44, v84, v85
	v_max3_f32 v36, v28, v86, v87
	ds_read_b128 v[28:31], v171 offset:23040
	v_max3_f32 v36, v36, v80, v81
	v_max3_f32 v44, v36, v82, v83
	s_waitcnt lgkmcnt(3)
	v_mfma_f32_16x16x32_f16 v[48:51], v[40:43], v[20:23], v[32:35]
	ds_read_b128 v[36:39], v171 offset:23104
	s_nop 1
	v_max3_f32 v32, v44, v76, v77
	v_max3_f32 v40, v32, v78, v79
	ds_read_b128 v[32:35], v171 offset:25344
	v_max3_f32 v40, v40, v72, v73
	v_max3_f32 v154, v40, v74, v75
	ds_read_b128 v[40:43], v171 offset:25408
	s_waitcnt lgkmcnt(3)
	v_mfma_f32_16x16x32_f16 v[28:31], v[28:31], v[24:27], 0
	s_waitcnt lgkmcnt(2)
	v_mfma_f32_16x16x32_f16 v[44:47], v[36:39], v[20:23], v[28:31]
	s_waitcnt lgkmcnt(1)
	v_mfma_f32_16x16x32_f16 v[32:35], v[32:35], v[24:27], 0
	s_nop 3
	v_max3_f32 v28, v154, v68, v69
	v_max3_f32 v36, v28, v70, v71
	v_max3_f32 v36, v36, v64, v65
	v_max3_f32 v154, v36, v66, v67
	s_waitcnt lgkmcnt(0)
	v_mfma_f32_16x16x32_f16 v[40:43], v[40:43], v[20:23], v[32:35]
	ds_read_b128 v[36:39], v171 offset:27712
	ds_read_b128 v[28:31], v171 offset:27648
	s_nop 0
	v_max3_f32 v32, v154, v60, v61
	v_max3_f32 v154, v32, v62, v63
	ds_read_b128 v[32:35], v171 offset:29952
	s_waitcnt lgkmcnt(0)
	v_mfma_f32_16x16x32_f16 v[32:35], v[32:35], v[24:27], 0
	v_max3_f32 v154, v154, v56, v57
	v_max3_f32 v154, v154, v58, v59
	v_mfma_f32_16x16x32_f16 v[32:35], v[162:165], v[20:23], v[32:35]
	ds_read_b128 v[162:165], v171 offset:34560
	v_mfma_f32_16x16x32_f16 v[28:31], v[28:31], v[24:27], 0
	v_mfma_f32_16x16x32_f16 v[36:39], v[36:39], v[20:23], v[28:31]
	s_nop 6
	v_max3_f32 v28, v154, v52, v53
	v_max3_f32 v154, v28, v54, v55
	ds_read_b128 v[28:31], v171 offset:32256
	ds_read_b128 v[170:173], v171 offset:34624
	v_max3_f32 v154, v154, v48, v49
	v_max3_f32 v154, v154, v50, v51
	v_max3_f32 v154, v154, v44, v45
	s_waitcnt lgkmcnt(1)
	v_mfma_f32_16x16x32_f16 v[28:31], v[28:31], v[24:27], 0
	v_max3_f32 v154, v154, v46, v47
	v_max3_f32 v154, v154, v40, v41
	v_max3_f32 v154, v154, v42, v43
	v_mfma_f32_16x16x32_f16 v[24:27], v[162:165], v[24:27], 0
	v_max3_f32 v154, v154, v36, v37
	v_max3_f32 v154, v154, v38, v39
	v_max3_f32 v154, v154, v32, v33
	v_mfma_f32_16x16x32_f16 v[28:31], v[166:169], v[20:23], v[28:31]
	v_max3_f32 v154, v154, v34, v35
	s_waitcnt lgkmcnt(0)
	v_mfma_f32_16x16x32_f16 v[20:23], v[170:173], v[20:23], v[24:27]
	s_nop 4
	v_max3_f32 v154, v154, v28, v29
	v_max3_f32 v154, v154, v30, v31
	s_nop 0
	v_max3_f32 v24, v154, v20, v21
	v_max3_f32 v24, v24, v22, v23
	ds_bpermute_b32 v25, v113, v24
	s_waitcnt lgkmcnt(0)
	v_max_f32_e32 v25, v25, v25
	v_max_f32_e32 v24, v24, v25
	ds_bpermute_b32 v25, v112, v24
	s_waitcnt lgkmcnt(0)
	v_max_f32_e32 v25, v25, v25
	v_max_f32_e32 v227, v24, v25
	v_sub_f32_e32 v24, v127, v227
	v_exp_f32_e32 v177, v24
	v_sub_f32_e32 v24, v128, v227
	v_exp_f32_e32 v179, v24
	v_sub_f32_e32 v24, v129, v227
	v_exp_f32_e32 v181, v24
	v_sub_f32_e32 v24, v130, v227
	v_exp_f32_e32 v183, v24
	v_sub_f32_e32 v25, v131, v227
	v_add_f32_e32 v24, 0, v177
	v_exp_f32_e32 v188, v25
	v_sub_f32_e32 v25, v132, v227
	v_add_f32_e32 v24, v179, v24
	v_exp_f32_e32 v189, v25
	v_sub_f32_e32 v25, v133, v227
	v_add_f32_e32 v24, v181, v24
	v_exp_f32_e32 v190, v25
	v_sub_f32_e32 v25, v134, v227
	v_add_f32_e32 v24, v183, v24
	v_exp_f32_e32 v191, v25
	v_sub_f32_e32 v25, v136, v227
	v_add_f32_e32 v24, v188, v24
	v_exp_f32_e32 v168, v25
	v_sub_f32_e32 v25, v137, v227
	v_add_f32_e32 v24, v189, v24
	v_exp_f32_e32 v170, v25
	v_sub_f32_e32 v25, v138, v227
	v_add_f32_e32 v24, v190, v24
	v_exp_f32_e32 v172, v25
	v_sub_f32_e32 v25, v139, v227
	v_add_f32_e32 v24, v191, v24
	v_exp_f32_e32 v174, v25
	v_sub_f32_e32 v25, v135, v227
	v_add_f32_e32 v24, v168, v24
	v_exp_f32_e32 v184, v25
	v_sub_f32_e32 v25, v140, v227
	v_add_f32_e32 v24, v170, v24
	v_exp_f32_e32 v185, v25
	v_sub_f32_e32 v25, v142, v227
	v_add_f32_e32 v24, v172, v24
	v_exp_f32_e32 v186, v25
	v_sub_f32_e32 v25, v141, v227
	v_add_f32_e32 v24, v174, v24
	v_exp_f32_e32 v187, v25
	v_sub_f32_e32 v25, v143, v227
	v_add_f32_e32 v24, v184, v24
	v_exp_f32_e32 v160, v25
	v_sub_f32_e32 v25, v144, v227
	v_add_f32_e32 v24, v185, v24
	v_exp_f32_e32 v162, v25
	v_sub_f32_e32 v25, v145, v227
	v_add_f32_e32 v24, v186, v24
	v_exp_f32_e32 v164, v25
	v_sub_f32_e32 v25, v146, v227
	v_add_f32_e32 v24, v187, v24
	v_exp_f32_e32 v166, v25
	v_sub_f32_e32 v25, v147, v227
	v_add_f32_e32 v24, v160, v24
	v_exp_f32_e32 v175, v25
	v_sub_f32_e32 v25, v148, v227
	v_add_f32_e32 v24, v162, v24
	v_exp_f32_e32 v178, v25
	v_sub_f32_e32 v25, v149, v227
	v_add_f32_e32 v24, v164, v24
	v_exp_f32_e32 v180, v25
	v_sub_f32_e32 v25, v150, v227
	v_add_f32_e32 v24, v166, v24
	v_exp_f32_e32 v182, v25
	v_sub_f32_e32 v25, v152, v227
	v_add_f32_e32 v24, v175, v24
	v_exp_f32_e32 v152, v25
	v_sub_f32_e32 v25, v153, v227
	v_add_f32_e32 v24, v178, v24
	v_exp_f32_e32 v154, v25
	v_sub_f32_e32 v25, v155, v227
	v_add_f32_e32 v24, v180, v24
	v_exp_f32_e32 v156, v25
	v_sub_f32_e32 v25, v157, v227
	v_add_f32_e32 v24, v182, v24
	v_exp_f32_e32 v158, v25
	v_sub_f32_e32 v25, v151, v227
	v_add_f32_e32 v24, v152, v24
	v_exp_f32_e32 v167, v25
	v_sub_f32_e32 v25, v159, v227
	v_add_f32_e32 v24, v154, v24
	v_exp_f32_e32 v169, v25
	v_sub_f32_e32 v25, v192, v227
	v_add_f32_e32 v24, v156, v24
	v_exp_f32_e32 v171, v25
	v_sub_f32_e32 v25, v161, v227
	v_add_f32_e32 v24, v158, v24
	v_exp_f32_e32 v173, v25
	v_sub_f32_e32 v25, v193, v227
	v_add_f32_e32 v24, v167, v24
	v_exp_f32_e32 v144, v25
	v_sub_f32_e32 v25, v194, v227
	v_add_f32_e32 v24, v169, v24
	v_exp_f32_e32 v146, v25
	v_sub_f32_e32 v25, v195, v227
	v_add_f32_e32 v24, v171, v24
	v_exp_f32_e32 v148, v25
	v_sub_f32_e32 v25, v196, v227
	v_add_f32_e32 v24, v173, v24
	v_exp_f32_e32 v150, v25
	v_sub_f32_e32 v25, v197, v227
	v_add_f32_e32 v24, v144, v24
	v_exp_f32_e32 v159, v25
	v_sub_f32_e32 v25, v198, v227
	v_add_f32_e32 v24, v146, v24
	v_exp_f32_e32 v161, v25
	v_sub_f32_e32 v25, v199, v227
	v_add_f32_e32 v24, v148, v24
	v_exp_f32_e32 v163, v25
	v_sub_f32_e32 v25, v200, v227
	v_add_f32_e32 v24, v150, v24
	v_exp_f32_e32 v165, v25
	v_sub_f32_e32 v25, v201, v227
	v_add_f32_e32 v24, v159, v24
	v_exp_f32_e32 v136, v25
	v_sub_f32_e32 v25, v202, v227
	v_add_f32_e32 v24, v161, v24
	v_exp_f32_e32 v138, v25
	v_sub_f32_e32 v25, v203, v227
	v_add_f32_e32 v24, v163, v24
	v_exp_f32_e32 v140, v25
	v_sub_f32_e32 v25, v206, v227
	v_add_f32_e32 v24, v165, v24
	v_exp_f32_e32 v142, v25
	v_sub_f32_e32 v25, v207, v227
	v_add_f32_e32 v24, v136, v24
	v_exp_f32_e32 v151, v25
	v_sub_f32_e32 v25, v208, v227
	v_add_f32_e32 v24, v138, v24
	v_exp_f32_e32 v153, v25
	v_sub_f32_e32 v25, v209, v227
	v_add_f32_e32 v24, v140, v24
	v_exp_f32_e32 v155, v25
	v_sub_f32_e32 v25, v210, v227
	v_add_f32_e32 v24, v142, v24
	v_exp_f32_e32 v157, v25
	v_sub_f32_e32 v25, v211, v227
	v_add_f32_e32 v24, v151, v24
	v_exp_f32_e32 v131, v25
	v_sub_f32_e32 v25, v212, v227
	v_add_f32_e32 v24, v153, v24
	v_exp_f32_e32 v132, v25
	v_sub_f32_e32 v25, v213, v227
	v_add_f32_e32 v24, v155, v24
	v_exp_f32_e32 v133, v25
	v_sub_f32_e32 v25, v214, v227
	v_add_f32_e32 v24, v157, v24
	v_exp_f32_e32 v134, v25
	v_sub_f32_e32 v25, v215, v227
	v_add_f32_e32 v24, v131, v24
	v_exp_f32_e32 v143, v25
	v_sub_f32_e32 v25, v216, v227
	v_add_f32_e32 v24, v132, v24
	v_exp_f32_e32 v145, v25
	v_sub_f32_e32 v25, v217, v227
	v_add_f32_e32 v24, v133, v24
	v_exp_f32_e32 v147, v25
	v_sub_f32_e32 v25, v218, v227
	v_add_f32_e32 v24, v134, v24
	v_exp_f32_e32 v149, v25
	v_sub_f32_e32 v25, v219, v227
	v_add_f32_e32 v24, v143, v24
	v_exp_f32_e32 v127, v25
	v_sub_f32_e32 v25, v220, v227
	v_add_f32_e32 v24, v145, v24
	v_exp_f32_e32 v128, v25
	v_sub_f32_e32 v25, v221, v227
	v_add_f32_e32 v24, v147, v24
	v_exp_f32_e32 v129, v25
	v_sub_f32_e32 v25, v222, v227
	v_add_f32_e32 v24, v149, v24
	v_exp_f32_e32 v130, v25
	v_sub_f32_e32 v25, v223, v227
	v_add_f32_e32 v24, v127, v24
	v_exp_f32_e32 v135, v25
	v_sub_f32_e32 v25, v224, v227
	v_add_f32_e32 v24, v128, v24
	v_exp_f32_e32 v137, v25
	v_sub_f32_e32 v25, v225, v227
	v_ashrrev_i32_e32 v241, 9, v111
	v_add_u32_e32 v242, s41, v241
	v_min_i32_e32 v242, 0x7f, v242
	v_lshl_add_u32 v244, v242, 6, v110
	v_ashrrev_i32_e32 v242, 9, v116
	v_add_u32_e32 v111, s41, v242
	v_min_i32_e32 v111, 0x7f, v111
	s_add_u32 s0, s14, s44
	v_lshl_add_u32 v192, v111, 6, v110
	s_addc_u32 s1, s15, 0
	v_ashrrev_i32_e32 v245, 31, v244
	v_ashrrev_i32_e32 v193, 31, v192
	v_lshl_add_u64 v[222:223], s[0:1], 0, v[88:89]
	v_lshlrev_b64 v[244:245], 11, v[244:245]
	v_lshlrev_b64 v[192:193], 11, v[192:193]
	v_lshl_add_u64 v[244:245], v[222:223], 0, v[244:245]
	v_lshl_add_u64 v[196:197], v[222:223], 0, v[192:193]
	v_ashrrev_i32_e32 v111, 9, v118
	global_load_dwordx4 v[192:195], v[244:245], off
	s_nop 0
	global_load_dwordx4 v[196:199], v[196:197], off
	v_add_u32_e32 v244, s41, v111
	v_min_i32_e32 v244, 0x7f, v244
	v_lshl_add_u32 v244, v244, 6, v110
	v_ashrrev_i32_e32 v245, 31, v244
	v_lshlrev_b64 v[244:245], 11, v[244:245]
	v_lshl_add_u64 v[200:201], v[222:223], 0, v[244:245]
	v_ashrrev_i32_e32 v244, 9, v120
	v_add_u32_e32 v245, s41, v244
	v_min_i32_e32 v245, 0x7f, v245
	v_lshl_add_u32 v202, v245, 6, v110
	v_ashrrev_i32_e32 v245, 9, v121
	v_add_u32_e32 v116, s41, v245
	v_min_i32_e32 v116, 0x7f, v116
	v_lshl_add_u32 v120, v116, 6, v110
	v_ashrrev_i32_e32 v203, 31, v202
	v_ashrrev_i32_e32 v121, 31, v120
	v_lshlrev_b64 v[202:203], 11, v[202:203]
	v_lshlrev_b64 v[120:121], 11, v[120:121]
	v_lshl_add_u64 v[206:207], v[222:223], 0, v[202:203]
	v_lshl_add_u64 v[120:121], v[222:223], 0, v[120:121]
	v_lshl_add_u64 v[98:99], v[222:223], 0, v[98:99]
	v_lshl_add_u64 v[96:97], v[222:223], 0, v[96:97]
	global_load_dwordx4 v[200:203], v[200:201], off
	s_nop 0
	global_load_dwordx4 v[206:209], v[206:207], off
	s_nop 0
	global_load_dwordx4 v[210:213], v[120:121], off
	global_load_dwordx4 v[214:217], v[98:99], off
	v_lshl_add_u64 v[98:99], v[222:223], 0, v[94:95]
	global_load_dwordx4 v[94:97], v[96:97], off
	s_nop 0
	global_load_dwordx4 v[218:221], v[98:99], off
	v_lshl_add_u64 v[92:93], v[222:223], 0, v[92:93]
	global_load_dwordx4 v[222:225], v[92:93], off
	v_add_f32_e32 v24, v129, v24
	v_exp_f32_e32 v139, v25
	v_sub_f32_e32 v25, v226, v227
	v_add_f32_e32 v24, v130, v24
	v_exp_f32_e32 v141, v25
	v_sub_f32_e32 v25, v84, v227
	v_add_f32_e32 v24, v135, v24
	v_exp_f32_e32 v84, v25
	v_sub_f32_e32 v25, v85, v227
	v_add_f32_e32 v24, v137, v24
	v_exp_f32_e32 v85, v25
	v_sub_f32_e32 v25, v86, v227
	v_add_f32_e32 v24, v139, v24
	v_exp_f32_e32 v86, v25
	v_sub_f32_e32 v25, v87, v227
	v_add_f32_e32 v24, v141, v24
	v_exp_f32_e32 v87, v25
	v_sub_f32_e32 v25, v80, v227
	v_add_f32_e32 v24, v84, v24
	v_exp_f32_e32 v80, v25
	v_sub_f32_e32 v25, v81, v227
	v_add_f32_e32 v24, v85, v24
	v_exp_f32_e32 v81, v25
	v_sub_f32_e32 v25, v82, v227
	v_add_f32_e32 v24, v86, v24
	v_exp_f32_e32 v82, v25
	v_sub_f32_e32 v25, v83, v227
	v_add_f32_e32 v24, v87, v24
	v_exp_f32_e32 v83, v25
	v_sub_f32_e32 v25, v76, v227
	v_add_f32_e32 v24, v80, v24
	v_exp_f32_e32 v76, v25
	v_sub_f32_e32 v25, v77, v227
	v_add_f32_e32 v24, v81, v24
	v_exp_f32_e32 v77, v25
	v_sub_f32_e32 v25, v78, v227
	v_add_f32_e32 v24, v82, v24
	v_exp_f32_e32 v78, v25
	v_sub_f32_e32 v25, v79, v227
	v_add_f32_e32 v24, v83, v24
	v_exp_f32_e32 v79, v25
	v_sub_f32_e32 v25, v72, v227
	v_add_f32_e32 v24, v76, v24
	v_exp_f32_e32 v72, v25
	v_sub_f32_e32 v25, v73, v227
	v_add_f32_e32 v24, v77, v24
	v_exp_f32_e32 v73, v25
	v_sub_f32_e32 v25, v74, v227
	v_add_f32_e32 v24, v78, v24
	v_exp_f32_e32 v74, v25
	v_sub_f32_e32 v25, v75, v227
	v_add_f32_e32 v24, v79, v24
	v_exp_f32_e32 v75, v25
	v_sub_f32_e32 v25, v68, v227
	v_add_f32_e32 v24, v72, v24
	v_exp_f32_e32 v68, v25
	v_sub_f32_e32 v25, v69, v227
	v_add_f32_e32 v24, v73, v24
	v_exp_f32_e32 v69, v25
	v_sub_f32_e32 v25, v70, v227
	v_add_f32_e32 v24, v74, v24
	v_exp_f32_e32 v70, v25
	v_sub_f32_e32 v25, v71, v227
	v_add_f32_e32 v24, v75, v24
	v_exp_f32_e32 v71, v25
	v_sub_f32_e32 v25, v64, v227
	v_add_f32_e32 v24, v68, v24
	v_exp_f32_e32 v64, v25
	v_sub_f32_e32 v25, v65, v227
	v_add_f32_e32 v24, v69, v24
	v_exp_f32_e32 v65, v25
	v_sub_f32_e32 v25, v66, v227
	v_add_f32_e32 v24, v70, v24
	v_exp_f32_e32 v66, v25
	v_sub_f32_e32 v25, v67, v227
	v_add_f32_e32 v24, v71, v24
	v_exp_f32_e32 v67, v25
	v_sub_f32_e32 v25, v60, v227
	v_add_f32_e32 v24, v64, v24
	v_exp_f32_e32 v60, v25
	v_sub_f32_e32 v25, v61, v227
	v_add_f32_e32 v24, v65, v24
	v_exp_f32_e32 v61, v25
	v_sub_f32_e32 v25, v62, v227
	v_add_f32_e32 v24, v66, v24
	v_exp_f32_e32 v62, v25
	v_sub_f32_e32 v25, v63, v227
	v_add_f32_e32 v24, v67, v24
	v_exp_f32_e32 v63, v25
	v_sub_f32_e32 v25, v56, v227
	v_add_f32_e32 v24, v60, v24
	v_exp_f32_e32 v56, v25
	v_sub_f32_e32 v25, v57, v227
	v_add_f32_e32 v24, v61, v24
	v_exp_f32_e32 v57, v25
	v_sub_f32_e32 v25, v58, v227
	v_add_f32_e32 v24, v62, v24
	v_exp_f32_e32 v58, v25
	v_sub_f32_e32 v25, v59, v227
	v_add_f32_e32 v24, v63, v24
	v_exp_f32_e32 v59, v25
	v_sub_f32_e32 v25, v52, v227
	v_add_f32_e32 v24, v56, v24
	v_exp_f32_e32 v52, v25
	v_sub_f32_e32 v25, v53, v227
	v_add_f32_e32 v24, v57, v24
	v_exp_f32_e32 v53, v25
	v_sub_f32_e32 v25, v54, v227
	v_add_f32_e32 v24, v58, v24
	v_exp_f32_e32 v54, v25
	v_sub_f32_e32 v25, v55, v227
	v_add_f32_e32 v24, v59, v24
	v_exp_f32_e32 v55, v25
	v_sub_f32_e32 v25, v48, v227
	v_add_f32_e32 v24, v52, v24
	v_exp_f32_e32 v48, v25
	v_sub_f32_e32 v25, v49, v227
	v_add_f32_e32 v24, v53, v24
	v_exp_f32_e32 v49, v25
	v_sub_f32_e32 v25, v50, v227
	v_add_f32_e32 v24, v54, v24
	v_exp_f32_e32 v50, v25
	v_sub_f32_e32 v25, v51, v227
	v_add_f32_e32 v24, v55, v24
	v_exp_f32_e32 v51, v25
	v_sub_f32_e32 v25, v44, v227
	v_add_f32_e32 v24, v48, v24
	v_exp_f32_e32 v44, v25
	v_sub_f32_e32 v25, v45, v227
	v_add_f32_e32 v24, v49, v24
	v_exp_f32_e32 v45, v25
	v_sub_f32_e32 v25, v46, v227
	v_add_f32_e32 v24, v50, v24
	v_exp_f32_e32 v46, v25
	v_sub_f32_e32 v25, v47, v227
	v_add_f32_e32 v24, v51, v24
	v_exp_f32_e32 v47, v25
	v_sub_f32_e32 v25, v40, v227
	v_add_f32_e32 v24, v44, v24
	v_exp_f32_e32 v40, v25
	v_sub_f32_e32 v25, v41, v227
	v_add_f32_e32 v24, v45, v24
	v_exp_f32_e32 v41, v25
	v_sub_f32_e32 v25, v42, v227
	v_add_f32_e32 v24, v46, v24
	v_exp_f32_e32 v42, v25
	v_sub_f32_e32 v25, v43, v227
	v_add_f32_e32 v24, v47, v24
	v_exp_f32_e32 v43, v25
	v_sub_f32_e32 v25, v36, v227
	v_add_f32_e32 v24, v40, v24
	v_exp_f32_e32 v36, v25
	v_sub_f32_e32 v25, v37, v227
	v_add_f32_e32 v24, v41, v24
	v_exp_f32_e32 v37, v25
	v_sub_f32_e32 v25, v38, v227
	v_add_f32_e32 v24, v42, v24
	v_exp_f32_e32 v38, v25
	v_sub_f32_e32 v25, v39, v227
	v_add_f32_e32 v24, v43, v24
	v_exp_f32_e32 v39, v25
	v_sub_f32_e32 v25, v32, v227
	v_add_f32_e32 v24, v36, v24
	v_exp_f32_e32 v32, v25
	v_sub_f32_e32 v25, v33, v227
	v_add_f32_e32 v24, v37, v24
	v_exp_f32_e32 v33, v25
	v_sub_f32_e32 v25, v34, v227
	v_add_f32_e32 v24, v38, v24
	v_exp_f32_e32 v34, v25
	v_sub_f32_e32 v25, v35, v227
	v_add_f32_e32 v24, v39, v24
	v_exp_f32_e32 v35, v25
	v_add_f32_e32 v24, v32, v24
	v_add_f32_e32 v24, v33, v24
	v_add_f32_e32 v24, v34, v24
	v_add_f32_e32 v243, v35, v24
	v_sub_f32_e32 v24, v28, v227
	v_exp_f32_e32 v24, v24
	v_sub_f32_e32 v25, v29, v227
	v_exp_f32_e32 v25, v25
	v_sub_f32_e32 v26, v30, v227
	v_exp_f32_e32 v26, v26
	v_sub_f32_e32 v27, v31, v227
	v_exp_f32_e32 v27, v27
	v_add_f32_e32 v28, v24, v243
	v_add_f32_e32 v28, v25, v28
	v_add_f32_e32 v28, v26, v28
	v_sub_f32_e32 v20, v20, v227
	v_add_f32_e32 v29, v27, v28
	v_exp_f32_e32 v28, v20
	v_sub_f32_e32 v20, v21, v227
	v_exp_f32_e32 v21, v20
	v_sub_f32_e32 v20, v22, v227
	v_exp_f32_e32 v22, v20
	v_sub_f32_e32 v20, v23, v227
	v_exp_f32_e32 v23, v20
	v_add_f32_e32 v20, v28, v29
	v_add_f32_e32 v20, v21, v20
	v_add_f32_e32 v20, v22, v20
	v_add_f32_e32 v20, v23, v20
	ds_bpermute_b32 v29, v113, v20
	s_waitcnt lgkmcnt(0)
	v_add_f32_e32 v20, v20, v29
	ds_bpermute_b32 v29, v112, v20
	v_mov_b32_e32 v30, v241
	v_mov_b32_e32 v31, v242
	v_mov_b32_e32 v112, v244
	v_mov_b32_e32 v113, v245
	s_waitcnt lgkmcnt(0)
	s_barrier
	s_waitcnt vmcnt(8)
	ds_write_b128 v114, v[192:195]
	s_waitcnt vmcnt(7)
	ds_write_b128 v115, v[196:199]
	s_waitcnt vmcnt(6)
	ds_write_b128 v117, v[200:203]
	s_waitcnt vmcnt(5)
	ds_write_b128 v119, v[206:209]
	s_waitcnt vmcnt(4)
	ds_write_b128 v122, v[210:213]
	s_waitcnt vmcnt(3)
	ds_write_b128 v123, v[214:217]
	s_waitcnt vmcnt(2)
	ds_write_b128 v124, v[94:97]
	s_waitcnt vmcnt(1)
	ds_write_b128 v125, v[218:221]
	s_waitcnt vmcnt(0)
	ds_write_b128 v126, v[222:225]
	s_add_i32 s41, s97, s9
	s_waitcnt lgkmcnt(0)
	s_barrier
	s_cmpk_gt_i32 s41, 0x7ff
	s_cselect_b64 s[0:1], -1, 0
	s_and_b64 vcc, exec, s[0:1]
	s_cbranch_vccnz .LBB0_1405
	s_mov_b64 s[2:3], -1
	s_and_b64 vcc, exec, s[10:11]
	s_cbranch_vccz .LBB0_1422
	s_and_b32 s50, s41, 63
	s_ashr_i32 s44, s41, 6
	s_mov_b64 s[2:3], 0
